# attention: two staging register sets (P aliases S), K/V tile loads issued two tiles ahead, counted vmcnt waits
# speedup vs baseline: 1.0069x; 1.0066x over previous
.LBB0_316:
	v_readlane_b32 s4, v251, 48
	v_readlane_b32 s34, v253, 15
	v_mbcnt_lo_u32_b32 v0, -1, 0
	v_mbcnt_hi_u32_b32 v0, -1, v0
	s_lshr_b32 s36, s4, 2
	s_and_b32 s31, s4, 3
	s_lshr_b32 s29, s36, 3
	s_and_b32 s30, s36, 7
	s_lshr_b32 s34, s34, 6
	s_lshr_b32 s35, s34, 2
	v_and_b32_e32 v240, 31, v0
	v_lshrrev_b32_e32 v241, 5, v0
	v_lshl_add_u32 v247, s34, 6, v0
	v_lshrrev_b32_e32 v248, 4, v247
	v_and_b32_e32 v249, 15, v247
	v_lshlrev_b32_e32 v220, 11, v248
	v_lshl_add_u32 v220, v249, 4, v220
	v_mul_u32_u24_e32 v225, 0x190, v248
	v_lshl_add_u32 v225, v249, 4, v225
	v_lshrrev_b32_e32 v248, 3, v247
	v_and_b32_e32 v249, 7, v247
	v_lshlrev_b32_e32 v221, 7, v248
	v_lshl_add_u32 v221, v249, 4, v221
	v_mul_u32_u24_e32 v226, 0x190, v248
	v_lshl_add_u32 v226, v249, 4, v226
	v_add_u32_e32 v226, 0x100, v226
	v_mul_u32_u24_e32 v222, 0x8200, v248
	v_lshl_add_u32 v222, v249, 4, v222
	v_mul_u32_u24_e32 v227, 0x88, v248
	v_lshl_add_u32 v227, v249, 4, v227
	v_add_u32_e32 v227, 0x12c00, v227
	v_add_u32_e32 v228, 0x2200, v227
	v_lshlrev_b32_e32 v229, 2, v0
	v_add_u32_e32 v229, 0x1f800, v229
	v_mul_u32_u24_e32 v230, 0x190, v240
	v_lshl_add_u32 v230, v241, 4, v230
	v_mul_u32_u24_e32 v231, 0x88, v240
	v_lshl_add_u32 v231, v241, 3, v231
	v_add_u32_e32 v231, 0x12c00, v231
	v_lshlrev_b32_e32 v232, 4, v241
	v_add_u32_e32 v232, 0x1f800, v232
	v_xor_b32_e32 v233, 32, v0
	v_lshlrev_b32_e32 v233, 2, v233
	v_mov_b32_e32 v238, 0xf149f2ca
	s_mov_b32 s26, 0
	s_mul_i32 s38, s29, 0x810
	s_mul_i32 s36, s30, 0x180
	s_add_u32 s40, s50, s36
	s_addc_u32 s41, s51, 0
	s_lshl_b32 s36, s30, 8
	s_add_u32 s36, s36, 0xc380000
	s_add_u32 s6, s48, s36
	s_addc_u32 s7, s49, 0
.Lat_item:
	s_sub_i32 s36, 8, s31
	s_add_i32 s37, s31, 1
	s_cmp_eq_u32 s26, 0
	s_cselect_b32 s36, s36, s37
	s_cmp_eq_u32 s26, 2
	s_cselect_b32 s36, 0, s36
	s_lshl_b32 s27, s36, 8
	s_sub_i32 s27, s27, 0xf0
	s_cmp_eq_u32 s36, 0
	s_cselect_b32 s27, 0, s27
	s_cselect_b32 s28, 16, 0x100
	s_add_i32 s23, s27, s28
	s_add_i32 s23, s23, 63
	s_lshr_b32 s23, s23, 6
	s_lshl_b32 s65, s34, 5
	s_add_i32 s64, s65, s27
	s_add_i32 s25, s64, 31
	s_lshr_b32 s25, s25, 6
	s_cmp_lt_u32 s65, s28
	s_cselect_b32 s25, s25, -1
	v_add_u32_e32 v234, s64, v240
	v_lshlrev_b32_e32 v0, 2, v241
	v_sub_u32_e32 v239, v234, v0
	s_cmp_lg_u32 s26, 0
	s_cbranch_scc1 .Lat_item_nofetch
	s_mov_b32 s4, s27
	s_lshl_b32 s65, s34, 5
	s_add_i32 s5, s65, s4
	v_add_u32_e32 v0, s5, v240
	v_min_u32_e32 v0, 0x80f, v0
	v_add_u32_e32 v0, s38, v0
	s_movk_i32 s39, 0xc00
	v_mul_lo_u32 v247, v0, s39
	v_lshl_add_u32 v247, v241, 4, v247
	v_lshlrev_b32_e32 v242, 5, v0
	global_load_dwordx4 v[98:101], v247, s[40:41]
	global_load_dwordx4 v[102:105], v247, s[40:41] offset:32
	global_load_dwordx4 v[106:109], v247, s[40:41] offset:64
	global_load_dwordx4 v[110:113], v247, s[40:41] offset:96
	global_load_dwordx4 v[114:117], v247, s[40:41] offset:128
	global_load_dwordx4 v[118:121], v247, s[40:41] offset:160
	global_load_dwordx4 v[122:125], v247, s[40:41] offset:192
	global_load_dwordx4 v[126:129], v247, s[40:41] offset:224
	global_load_dwordx4 v[130:133], v247, s[40:41] offset:256
	global_load_dwordx4 v[134:137], v247, s[40:41] offset:288
	global_load_dwordx4 v[138:141], v247, s[40:41] offset:320
	global_load_dwordx4 v[142:145], v247, s[40:41] offset:352
	s_lshl_b32 s36, s30, 2
	s_add_u32 s36, s36, 0x1507a400
	s_add_u32 s36, s48, s36
	s_addc_u32 s37, s49, 0
	global_load_dword v249, v242, s[36:37]
	s_lshl_b32 s73, s38, 11
	s_add_u32 s72, s73, 0x10480000
	s_lshl_b32 s73, s30, 8
	s_add_u32 s72, s72, s73
	s_add_u32 s8, s48, s72
	s_addc_u32 s9, s49, 0
	s_add_u32 s10, s8, 0x10000
	s_addc_u32 s11, s9, 0
	s_lshl_b32 s73, s38, 7
	s_add_u32 s72, s73, 0x14da0000
	s_add_u32 s12, s48, s72
	s_addc_u32 s13, s49, 0
	s_mul_i32 s73, s30, 0x410000
	s_lshl_b32 s72, s38, 1
	s_add_u32 s72, s72, s73
	s_add_u32 s72, s72, 0x12500000
	s_add_u32 s14, s48, s72
	s_addc_u32 s15, s49, 0
	s_add_u32 s16, s14, 0x208000
	s_addc_u32 s17, s15, 0
	s_lshl_b32 s73, s38, 5
	s_add_u32 s72, s73, 0x150fc400
	s_lshl_b32 s73, s30, 2
	s_add_u32 s72, s72, s73
	s_add_u32 s18, s48, s72
	s_addc_u32 s19, s49, 0
	s_lshl_b32 s73, s38, 2
	s_add_u32 s72, s73, 0x1506a000
	s_add_u32 s20, s48, s72
	s_addc_u32 s21, s49, 0
	global_load_dwordx4 v[198:201], v220, s[8:9]
	global_load_dwordx4 v[202:205], v220, s[10:11]
	global_load_dwordx4 v[206:209], v221, s[12:13]
	global_load_dwordx4 v[210:213], v222, s[14:15]
	global_load_dwordx4 v[214:217], v222, s[16:17]
	s_cmp_lg_u32 s34, 0
	s_cbranch_scc1 .Lat_nosq1
	v_lshl_add_u32 v247, v241, 5, v240
	v_lshlrev_b32_e32 v242, 2, v247
	v_lshlrev_b32_e32 v247, 5, v247
	global_load_dword v218, v247, s[18:19]
	global_load_dword v219, v242, s[20:21]

.Lat_item_nobar:
	s_cmp_lt_u32 s23, 2
	s_cbranch_scc1 .Lat_h_one
	s_add_u32 s8, s8, 0x20000
	s_addc_u32 s9, s9, 0
	s_add_u32 s10, s10, 0x20000
	s_addc_u32 s11, s11, 0
	s_add_u32 s12, s12, 0x2000
	s_addc_u32 s13, s13, 0
	s_add_u32 s14, s14, 0x80
	s_addc_u32 s15, s15, 0
	s_add_u32 s16, s16, 0x80
	s_addc_u32 s17, s17, 0
	s_add_u32 s18, s18, 0x800
	s_addc_u32 s19, s19, 0
	s_add_u32 s20, s20, 0x100
	s_addc_u32 s21, s21, 0
	global_load_dwordx4 v[146:149], v220, s[8:9]
	global_load_dwordx4 v[150:153], v220, s[10:11]
	global_load_dwordx4 v[154:157], v221, s[12:13]
	global_load_dwordx4 v[158:161], v222, s[14:15]
	global_load_dwordx4 v[194:197], v222, s[16:17]
	s_cmp_lg_u32 s34, 0
	s_cbranch_scc1 .Lat_nosq2
	v_lshl_add_u32 v247, v241, 5, v240
	v_lshlrev_b32_e32 v242, 2, v247
	v_lshlrev_b32_e32 v247, 5, v247
	global_load_dword v223, v247, s[18:19]
	global_load_dword v224, v242, s[20:21]
.Lat_nosq2:
	s_cmp_eq_u32 s34, 0
	s_cbranch_scc1 .Lat_w7_3
	s_waitcnt vmcnt(5)
	s_branch .Lat_wd_3
.Lat_w7_3:
	s_waitcnt vmcnt(7)
.Lat_wd_3:
	s_branch .Lat_h_w
.Lat_h_one:
	s_waitcnt vmcnt(0)
.Lat_h_w:
	s_mov_b32 s36, 0
	s_mov_b32 s37, 0
	s_mov_b32 s39, 0
	v_add_u32_e32 v0, s36, v225
	ds_write_b128 v0, v[198:201]
	ds_write_b128 v0, v[202:205] offset:12800
	v_add_u32_e32 v0, s36, v226
	ds_write_b128 v0, v[206:209]
	v_add_u32_e32 v0, s37, v227
	ds_write2_b64 v0, v[210:211], v[212:213] offset1:1
	v_add_u32_e32 v0, s37, v228
	ds_write2_b64 v0, v[214:215], v[216:217] offset1:1
	s_cmp_lg_u32 s34, 0
	s_cbranch_scc1 .Lat_nosc5
	v_add_f32_e32 v247, v218, v219
	v_mov_b32_e32 v242, 0x358637bd
	v_fmamk_f32 v247, v247, 0x3baaaaab, v242
	v_rsq_f32_e32 v247, v247
	v_add_u32_e32 v0, s39, v229
	s_nop 0
	ds_write_b32 v0, v247
.Lat_nosc5:
	v_mov_b32_e32 v242, 0x358637bd
	v_fmamk_f32 v235, v249, 0x3baaaaab, v242
	v_rsq_f32_e32 v235, v235
	s_nop 0
	v_mul_f32_e32 v235, 0x3dd53b95, v235
	s_cmp_lt_u32 s23, 3
	s_cbranch_scc1 .Lat_no_t2
	s_add_u32 s8, s8, 0x20000
	s_addc_u32 s9, s9, 0
	s_add_u32 s10, s10, 0x20000
	s_addc_u32 s11, s11, 0
	s_add_u32 s12, s12, 0x2000
	s_addc_u32 s13, s13, 0
	s_add_u32 s14, s14, 0x80
	s_addc_u32 s15, s15, 0
	s_add_u32 s16, s16, 0x80
	s_addc_u32 s17, s17, 0
	s_add_u32 s18, s18, 0x800
	s_addc_u32 s19, s19, 0
	s_add_u32 s20, s20, 0x100
	s_addc_u32 s21, s21, 0
	global_load_dwordx4 v[198:201], v220, s[8:9]
	global_load_dwordx4 v[202:205], v220, s[10:11]
	global_load_dwordx4 v[206:209], v221, s[12:13]
	global_load_dwordx4 v[210:213], v222, s[14:15]
	global_load_dwordx4 v[214:217], v222, s[16:17]
	s_cmp_lg_u32 s34, 0
	s_cbranch_scc1 .Lat_nosq6
	v_lshl_add_u32 v247, v241, 5, v240
	v_lshlrev_b32_e32 v242, 2, v247
	v_lshlrev_b32_e32 v247, 5, v247
	global_load_dword v218, v247, s[18:19]
	global_load_dword v219, v242, s[20:21]

.Lat_loop:
	s_cmp_eq_u32 s35, 0
	s_cbranch_scc1 .Lat_yb_skip
	s_cmp_eq_u32 s22, 0
	s_cbranch_scc1 .Lat_yb_skip
	s_add_i32 s96, s22, -1
	s_cmp_gt_i32 s96, s25
	s_cbranch_scc1 .Lat_y_skip_b
	s_nop 7
	s_waitcnt lgkmcnt(0)
	v_mul_f32_e32 v66, v66, v162
	v_mul_f32_e32 v67, v67, v163
	v_mul_f32_e32 v68, v68, v164
	v_mul_f32_e32 v69, v69, v165
	v_mul_f32_e32 v70, v70, v166
	v_mul_f32_e32 v71, v71, v167
	v_mul_f32_e32 v72, v72, v168
	v_mul_f32_e32 v73, v73, v169
	v_mul_f32_e32 v74, v74, v170
	v_mul_f32_e32 v75, v75, v171
	v_mul_f32_e32 v76, v76, v172
	v_mul_f32_e32 v77, v77, v173
	v_mul_f32_e32 v78, v78, v174
	v_mul_f32_e32 v79, v79, v175
	v_mul_f32_e32 v80, v80, v176
	v_mul_f32_e32 v81, v81, v177
	v_mul_f32_e32 v82, v82, v178
	v_mul_f32_e32 v83, v83, v179
	v_mul_f32_e32 v84, v84, v180
	v_mul_f32_e32 v85, v85, v181
	v_mul_f32_e32 v86, v86, v182
	v_mul_f32_e32 v87, v87, v183
	v_mul_f32_e32 v88, v88, v184
	v_mul_f32_e32 v89, v89, v185
	v_mul_f32_e32 v90, v90, v186
	v_mul_f32_e32 v91, v91, v187
	v_mul_f32_e32 v92, v92, v188
	v_mul_f32_e32 v93, v93, v189
	v_mul_f32_e32 v94, v94, v190
	v_mul_f32_e32 v95, v95, v191
	v_mul_f32_e32 v96, v96, v192
	v_mul_f32_e32 v97, v97, v193
	s_cmp_lg_u32 s96, s25
	s_cbranch_scc1 .Lat_y_nogate_b
	v_add_u32_e32 v243, s38, v234
	v_lshlrev_b32_e32 v243, 11, v243
	v_lshl_add_u32 v243, v241, 3, v243
	global_load_dwordx2 v[162:163], v243, s[6:7] offset:0
	global_load_dwordx2 v[164:165], v243, s[6:7] offset:16
	global_load_dwordx2 v[166:167], v243, s[6:7] offset:32
	global_load_dwordx2 v[168:169], v243, s[6:7] offset:48
	global_load_dwordx2 v[170:171], v243, s[6:7] offset:64
	global_load_dwordx2 v[172:173], v243, s[6:7] offset:80
	global_load_dwordx2 v[174:175], v243, s[6:7] offset:96
	global_load_dwordx2 v[176:177], v243, s[6:7] offset:112
	global_load_dwordx2 v[178:179], v243, s[6:7] offset:128
	global_load_dwordx2 v[180:181], v243, s[6:7] offset:144
	global_load_dwordx2 v[182:183], v243, s[6:7] offset:160
	global_load_dwordx2 v[184:185], v243, s[6:7] offset:176
	global_load_dwordx2 v[186:187], v243, s[6:7] offset:192
	global_load_dwordx2 v[188:189], v243, s[6:7] offset:208
	global_load_dwordx2 v[190:191], v243, s[6:7] offset:224
	global_load_dwordx2 v[192:193], v243, s[6:7] offset:240

.Lat_y_nomask_b:
	v_max3_f32 v247, v66, v67, v68
	v_max3_f32 v0, v82, v83, v84
	v_max3_f32 v247, v247, v69, v70
	v_max3_f32 v0, v0, v85, v86
	v_max3_f32 v247, v247, v71, v72
	v_max3_f32 v0, v0, v87, v88
	v_max3_f32 v247, v247, v73, v74
	v_max3_f32 v0, v0, v89, v90
	v_max3_f32 v247, v247, v75, v76
	v_max3_f32 v0, v0, v91, v92
	v_max3_f32 v247, v247, v77, v78
	v_max3_f32 v0, v0, v93, v94
	v_max3_f32 v247, v247, v79, v80
	v_max3_f32 v0, v0, v95, v96
	v_max3_f32 v247, v247, v81, v97
	v_max_f32_e32 v247, v247, v0
	v_mov_b32_e32 v0, v247
	s_nop 1
	v_permlane32_swap_b32_e32 v0, v247
	s_nop 1
	v_max_f32_e32 v247, v247, v0
	v_mul_f32_e32 v0, v235, v247
	v_sub_f32_e32 v243, v0, v236
	v_cmp_lt_f32_e32 vcc, 0x41000000, v243
	s_nop 1
	v_cndmask_b32_e32 v244, v236, v0, vcc
	v_sub_f32_e32 v248, v236, v244
	v_exp_f32_e32 v248, v248
	s_nop 0
	s_cbranch_vccz .Lat_y_norescale_b
	v_pk_mul_f32 v[2:3], v[2:3], v[248:249] op_sel_hi:[1,0]
	v_pk_mul_f32 v[4:5], v[4:5], v[248:249] op_sel_hi:[1,0]
	v_pk_mul_f32 v[6:7], v[6:7], v[248:249] op_sel_hi:[1,0]
	v_pk_mul_f32 v[8:9], v[8:9], v[248:249] op_sel_hi:[1,0]
	v_pk_mul_f32 v[10:11], v[10:11], v[248:249] op_sel_hi:[1,0]
	v_pk_mul_f32 v[12:13], v[12:13], v[248:249] op_sel_hi:[1,0]
	v_pk_mul_f32 v[14:15], v[14:15], v[248:249] op_sel_hi:[1,0]
	v_pk_mul_f32 v[16:17], v[16:17], v[248:249] op_sel_hi:[1,0]
	v_pk_mul_f32 v[18:19], v[18:19], v[248:249] op_sel_hi:[1,0]
	v_pk_mul_f32 v[20:21], v[20:21], v[248:249] op_sel_hi:[1,0]
	v_pk_mul_f32 v[22:23], v[22:23], v[248:249] op_sel_hi:[1,0]
	v_pk_mul_f32 v[24:25], v[24:25], v[248:249] op_sel_hi:[1,0]
	v_pk_mul_f32 v[26:27], v[26:27], v[248:249] op_sel_hi:[1,0]
	v_pk_mul_f32 v[28:29], v[28:29], v[248:249] op_sel_hi:[1,0]
	v_pk_mul_f32 v[30:31], v[30:31], v[248:249] op_sel_hi:[1,0]
	v_pk_mul_f32 v[32:33], v[32:33], v[248:249] op_sel_hi:[1,0]
	v_pk_mul_f32 v[34:35], v[34:35], v[248:249] op_sel_hi:[1,0]
	v_pk_mul_f32 v[36:37], v[36:37], v[248:249] op_sel_hi:[1,0]
	v_pk_mul_f32 v[38:39], v[38:39], v[248:249] op_sel_hi:[1,0]
	v_pk_mul_f32 v[40:41], v[40:41], v[248:249] op_sel_hi:[1,0]
	v_pk_mul_f32 v[42:43], v[42:43], v[248:249] op_sel_hi:[1,0]
	v_pk_mul_f32 v[44:45], v[44:45], v[248:249] op_sel_hi:[1,0]
	v_pk_mul_f32 v[46:47], v[46:47], v[248:249] op_sel_hi:[1,0]
	v_pk_mul_f32 v[48:49], v[48:49], v[248:249] op_sel_hi:[1,0]
	v_pk_mul_f32 v[50:51], v[50:51], v[248:249] op_sel_hi:[1,0]
	v_pk_mul_f32 v[52:53], v[52:53], v[248:249] op_sel_hi:[1,0]
	v_pk_mul_f32 v[54:55], v[54:55], v[248:249] op_sel_hi:[1,0]
	v_pk_mul_f32 v[56:57], v[56:57], v[248:249] op_sel_hi:[1,0]
	v_pk_mul_f32 v[58:59], v[58:59], v[248:249] op_sel_hi:[1,0]
	v_pk_mul_f32 v[60:61], v[60:61], v[248:249] op_sel_hi:[1,0]
	v_pk_mul_f32 v[62:63], v[62:63], v[248:249] op_sel_hi:[1,0]
	v_pk_mul_f32 v[64:65], v[64:65], v[248:249] op_sel_hi:[1,0]
.Lat_y_norescale_b:
	v_fma_f32 v66, v235, v66, -v244
	v_fma_f32 v67, v235, v67, -v244
	v_exp_f32_e32 v66, v66
	v_fma_f32 v68, v235, v68, -v244
	v_exp_f32_e32 v67, v67
	v_fma_f32 v69, v235, v69, -v244
	v_exp_f32_e32 v68, v68
	v_fma_f32 v70, v235, v70, -v244
	v_exp_f32_e32 v69, v69
	v_fma_f32 v71, v235, v71, -v244
	v_exp_f32_e32 v70, v70
	v_fma_f32 v72, v235, v72, -v244
	v_exp_f32_e32 v71, v71
	v_fma_f32 v73, v235, v73, -v244
	v_exp_f32_e32 v72, v72
	v_fma_f32 v74, v235, v74, -v244
	v_exp_f32_e32 v73, v73
	v_fma_f32 v75, v235, v75, -v244
	v_exp_f32_e32 v74, v74
	v_fma_f32 v76, v235, v76, -v244
	v_exp_f32_e32 v75, v75
	v_fma_f32 v77, v235, v77, -v244
	v_exp_f32_e32 v76, v76
	v_fma_f32 v78, v235, v78, -v244
	v_exp_f32_e32 v77, v77
	v_fma_f32 v79, v235, v79, -v244
	v_exp_f32_e32 v78, v78
	v_fma_f32 v80, v235, v80, -v244
	v_exp_f32_e32 v79, v79
	v_fma_f32 v81, v235, v81, -v244
	v_exp_f32_e32 v80, v80
	v_fma_f32 v82, v235, v82, -v244
	v_exp_f32_e32 v81, v81
	v_fma_f32 v83, v235, v83, -v244
	v_exp_f32_e32 v82, v82
	v_fma_f32 v84, v235, v84, -v244
	v_exp_f32_e32 v83, v83
	v_fma_f32 v85, v235, v85, -v244
	v_exp_f32_e32 v84, v84
	v_fma_f32 v86, v235, v86, -v244
	v_exp_f32_e32 v85, v85
	v_fma_f32 v87, v235, v87, -v244
	v_exp_f32_e32 v86, v86
	v_fma_f32 v88, v235, v88, -v244
	v_exp_f32_e32 v87, v87
	v_fma_f32 v89, v235, v89, -v244
	v_exp_f32_e32 v88, v88
	v_fma_f32 v90, v235, v90, -v244
	v_exp_f32_e32 v89, v89
	v_fma_f32 v91, v235, v91, -v244
	v_exp_f32_e32 v90, v90
	v_fma_f32 v92, v235, v92, -v244
	v_exp_f32_e32 v91, v91
	v_fma_f32 v93, v235, v93, -v244
	v_exp_f32_e32 v92, v92
	v_fma_f32 v94, v235, v94, -v244
	v_exp_f32_e32 v93, v93
	v_fma_f32 v95, v235, v95, -v244
	v_exp_f32_e32 v94, v94
	v_fma_f32 v96, v235, v96, -v244
	v_exp_f32_e32 v95, v95
	v_fma_f32 v97, v235, v97, -v244
	v_exp_f32_e32 v96, v96
	v_exp_f32_e32 v97, v97
	s_nop 0
	v_add_f32_e32 v245, v66, v70
	v_add_f32_e32 v246, v67, v71
	v_add_f32_e32 v247, v68, v72
	v_add_f32_e32 v0, v69, v73
	v_add_f32_e32 v245, v245, v74
	v_add_f32_e32 v246, v246, v75
	v_add_f32_e32 v247, v247, v76
	v_add_f32_e32 v0, v0, v77
	v_add_f32_e32 v245, v245, v78
	v_add_f32_e32 v246, v246, v79
	v_add_f32_e32 v247, v247, v80
	v_add_f32_e32 v0, v0, v81
	v_add_f32_e32 v245, v245, v82
	v_add_f32_e32 v246, v246, v83
	v_add_f32_e32 v247, v247, v84
	v_add_f32_e32 v0, v0, v85
	v_add_f32_e32 v245, v245, v86
	v_add_f32_e32 v246, v246, v87
	v_add_f32_e32 v247, v247, v88
	v_add_f32_e32 v0, v0, v89
	v_add_f32_e32 v245, v245, v90
	v_add_f32_e32 v246, v246, v91
	v_add_f32_e32 v247, v247, v92
	v_add_f32_e32 v0, v0, v93
	v_add_f32_e32 v245, v245, v94
	v_add_f32_e32 v246, v246, v95
	v_add_f32_e32 v247, v247, v96
	v_add_f32_e32 v0, v0, v97
	v_add_f32_e32 v245, v245, v246
	v_add_f32_e32 v247, v247, v0
	v_add_f32_e32 v245, v245, v247
	v_mov_b32_e32 v236, v244
	v_fma_f32 v237, v237, v248, v245
	v_cvt_pk_bf16_f32 v66, v66, v67
	v_cvt_pk_bf16_f32 v67, v68, v69
	v_cvt_pk_bf16_f32 v68, v70, v71
	v_cvt_pk_bf16_f32 v69, v72, v73
	v_cvt_pk_bf16_f32 v70, v74, v75
	v_cvt_pk_bf16_f32 v71, v76, v77
	v_cvt_pk_bf16_f32 v72, v78, v79
	v_cvt_pk_bf16_f32 v73, v80, v81
	v_cvt_pk_bf16_f32 v74, v82, v83
	v_cvt_pk_bf16_f32 v75, v84, v85
	v_cvt_pk_bf16_f32 v76, v86, v87
	v_cvt_pk_bf16_f32 v77, v88, v89
	v_cvt_pk_bf16_f32 v78, v90, v91
	v_cvt_pk_bf16_f32 v79, v92, v93
	v_cvt_pk_bf16_f32 v80, v94, v95
	v_cvt_pk_bf16_f32 v81, v96, v97
.Lat_y_skip_b:
.Lat_yb_skip:
	s_add_i32 s65, s22, 1
	s_cmp_ge_u32 s65, s23
	s_cbranch_scc1 .Lat_x_nostore
	s_add_i32 s72, s24, 1
	s_cmp_eq_u32 s72, 3
	s_cselect_b32 s72, 0, s72
	s_mul_i32 s36, s72, 0x6400
	s_mul_i32 s37, s72, 0x4400
	s_lshl_b32 s39, s72, 8
	s_add_i32 s72, s22, 2
	s_cmp_ge_u32 s72, s23
	s_cbranch_scc1 .Lat_x_wl
	s_cmp_eq_u32 s34, 0
	s_cbranch_scc1 .Lat_w7_7
	s_waitcnt vmcnt(5)
	s_branch .Lat_wd_7

.Lat_wd_7:
	s_branch .Lat_x_wd
.Lat_x_wl:
	s_waitcnt vmcnt(0)
.Lat_x_wd:
	s_bitcmp1_b32 s65, 0
	s_cbranch_scc1 .Lat_x_set1
	v_add_u32_e32 v0, s36, v225
	ds_write_b128 v0, v[198:201]
	ds_write_b128 v0, v[202:205] offset:12800
	v_add_u32_e32 v0, s36, v226
	ds_write_b128 v0, v[206:209]
	v_add_u32_e32 v0, s37, v227
	ds_write2_b64 v0, v[210:211], v[212:213] offset1:1
	v_add_u32_e32 v0, s37, v228
	ds_write2_b64 v0, v[214:215], v[216:217] offset1:1
	s_cmp_lg_u32 s34, 0
	s_cbranch_scc1 .Lat_nosc9
	v_add_f32_e32 v247, v218, v219
	v_mov_b32_e32 v242, 0x358637bd
	v_fmamk_f32 v247, v247, 0x3baaaaab, v242
	v_rsq_f32_e32 v247, v247
	v_add_u32_e32 v0, s39, v229
	s_nop 0
	ds_write_b32 v0, v247
.Lat_nosc9:
	s_add_i32 s65, s22, 3
	s_cmp_ge_u32 s65, s23
	s_cbranch_scc1 .Lat_x_nostore
	s_add_u32 s8, s8, 0x20000
	s_addc_u32 s9, s9, 0
	s_add_u32 s10, s10, 0x20000
	s_addc_u32 s11, s11, 0
	s_add_u32 s12, s12, 0x2000
	s_addc_u32 s13, s13, 0
	s_add_u32 s14, s14, 0x80
	s_addc_u32 s15, s15, 0
	s_add_u32 s16, s16, 0x80
	s_addc_u32 s17, s17, 0
	s_add_u32 s18, s18, 0x800
	s_addc_u32 s19, s19, 0
	s_add_u32 s20, s20, 0x100
	s_addc_u32 s21, s21, 0
	global_load_dwordx4 v[198:201], v220, s[8:9]
	global_load_dwordx4 v[202:205], v220, s[10:11]
	global_load_dwordx4 v[206:209], v221, s[12:13]
	global_load_dwordx4 v[210:213], v222, s[14:15]
	global_load_dwordx4 v[214:217], v222, s[16:17]
	s_cmp_lg_u32 s34, 0
	s_cbranch_scc1 .Lat_nosq10
	v_lshl_add_u32 v247, v241, 5, v240
	v_lshlrev_b32_e32 v242, 2, v247
	v_lshlrev_b32_e32 v247, 5, v247
	global_load_dword v218, v247, s[18:19]
	global_load_dword v219, v242, s[20:21]

.Lat_x_set1:
	v_add_u32_e32 v0, s36, v225
	ds_write_b128 v0, v[146:149]
	ds_write_b128 v0, v[150:153] offset:12800
	v_add_u32_e32 v0, s36, v226
	ds_write_b128 v0, v[154:157]
	v_add_u32_e32 v0, s37, v227
	ds_write2_b64 v0, v[158:159], v[160:161] offset1:1
	v_add_u32_e32 v0, s37, v228
	ds_write2_b64 v0, v[194:195], v[196:197] offset1:1
	s_cmp_lg_u32 s34, 0
	s_cbranch_scc1 .Lat_nosc11
	v_add_f32_e32 v247, v223, v224
	v_mov_b32_e32 v242, 0x358637bd
	v_fmamk_f32 v247, v247, 0x3baaaaab, v242
	v_rsq_f32_e32 v247, v247
	v_add_u32_e32 v0, s39, v229
	s_nop 0
	ds_write_b32 v0, v247
.Lat_nosc11:
	s_add_i32 s65, s22, 3
	s_cmp_ge_u32 s65, s23
	s_cbranch_scc1 .Lat_x_nostore
	s_add_u32 s8, s8, 0x20000
	s_addc_u32 s9, s9, 0
	s_add_u32 s10, s10, 0x20000
	s_addc_u32 s11, s11, 0
	s_add_u32 s12, s12, 0x2000
	s_addc_u32 s13, s13, 0
	s_add_u32 s14, s14, 0x80
	s_addc_u32 s15, s15, 0
	s_add_u32 s16, s16, 0x80
	s_addc_u32 s17, s17, 0
	s_add_u32 s18, s18, 0x800
	s_addc_u32 s19, s19, 0
	s_add_u32 s20, s20, 0x100
	s_addc_u32 s21, s21, 0
	global_load_dwordx4 v[146:149], v220, s[8:9]
	global_load_dwordx4 v[150:153], v220, s[10:11]
	global_load_dwordx4 v[154:157], v221, s[12:13]
	global_load_dwordx4 v[158:161], v222, s[14:15]
	global_load_dwordx4 v[194:197], v222, s[16:17]
	s_cmp_lg_u32 s34, 0
	s_cbranch_scc1 .Lat_nosq12
	v_lshl_add_u32 v247, v241, 5, v240
	v_lshlrev_b32_e32 v242, 2, v247
	v_lshlrev_b32_e32 v247, 5, v247
	global_load_dword v223, v247, s[18:19]
	global_load_dword v224, v242, s[20:21]
.Lat_nosq12:
.Lat_x_nostore:
	s_setprio 1
	s_cmp_gt_i32 s22, s25
	s_cbranch_scc1 .Lat_x_nopre
	s_mul_i32 s36, s24, 0x6400
	v_add_u32_e32 v0, s36, v230
	ds_read_b128 v[162:165], v0
	ds_read_b128 v[166:169], v0 offset:12800
	ds_read_b128 v[170:173], v0 offset:32
	ds_read_b128 v[174:177], v0 offset:12832
	ds_read_b128 v[178:181], v0 offset:64
	ds_read_b128 v[182:185], v0 offset:12864
.Lat_x_nopre:
	s_cmp_eq_u32 s22, 0
	s_cbranch_scc1 .Lat_x_nopv
	s_add_i32 s65, s22, -1
	s_cmp_gt_i32 s65, s25
	s_cbranch_scc1 .Lat_x_nopv
	s_add_i32 s72, s24, 2
	s_cmp_ge_u32 s72, 3
	s_cbranch_scc0 .Lat_x_pvb
	s_sub_i32 s72, s72, 3
.Lat_x_pvb:
	s_mul_i32 s37, s72, 0x4400
	v_add_u32_e32 v243, s37, v231
	v_add_u32_e32 v244, 0x1100, v243
	v_add_u32_e32 v245, 0x2200, v243
	v_add_u32_e32 v246, 0x3300, v243
	ds_read2_b64 v[82:85], v243 offset0:0 offset1:2
	ds_read2_b64 v[86:89], v244 offset0:0 offset1:2
	ds_read2_b64 v[90:93], v245 offset0:0 offset1:2
	s_waitcnt lgkmcnt(2)
	v_mfma_f32_32x32x16_bf16 v[2:17], v[82:85], v[66:69], v[2:17]
	ds_read2_b64 v[94:97], v246 offset0:0 offset1:2
	s_waitcnt lgkmcnt(2)
	v_mfma_f32_32x32x16_bf16 v[18:33], v[86:89], v[66:69], v[18:33]
	ds_read2_b64 v[82:85], v243 offset0:4 offset1:6
	s_waitcnt lgkmcnt(2)
	v_mfma_f32_32x32x16_bf16 v[34:49], v[90:93], v[66:69], v[34:49]
	ds_read2_b64 v[86:89], v244 offset0:4 offset1:6
	s_waitcnt lgkmcnt(2)
	v_mfma_f32_32x32x16_bf16 v[50:65], v[94:97], v[66:69], v[50:65]
	ds_read2_b64 v[90:93], v245 offset0:4 offset1:6
	s_waitcnt lgkmcnt(2)
	v_mfma_f32_32x32x16_bf16 v[2:17], v[82:85], v[70:73], v[2:17]
	ds_read2_b64 v[94:97], v246 offset0:4 offset1:6
	s_waitcnt lgkmcnt(2)
	v_mfma_f32_32x32x16_bf16 v[18:33], v[86:89], v[70:73], v[18:33]
	ds_read2_b64 v[82:85], v243 offset0:8 offset1:10
	s_waitcnt lgkmcnt(2)
	v_mfma_f32_32x32x16_bf16 v[34:49], v[90:93], v[70:73], v[34:49]
	ds_read2_b64 v[86:89], v244 offset0:8 offset1:10
	s_waitcnt lgkmcnt(2)
	v_mfma_f32_32x32x16_bf16 v[50:65], v[94:97], v[70:73], v[50:65]
	ds_read2_b64 v[90:93], v245 offset0:8 offset1:10
	s_waitcnt lgkmcnt(2)
	v_mfma_f32_32x32x16_bf16 v[2:17], v[82:85], v[74:77], v[2:17]
	ds_read2_b64 v[94:97], v246 offset0:8 offset1:10
	s_waitcnt lgkmcnt(2)
	v_mfma_f32_32x32x16_bf16 v[18:33], v[86:89], v[74:77], v[18:33]
	ds_read2_b64 v[82:85], v243 offset0:12 offset1:14
	s_waitcnt lgkmcnt(2)
	v_mfma_f32_32x32x16_bf16 v[34:49], v[90:93], v[74:77], v[34:49]
	ds_read2_b64 v[86:89], v244 offset0:12 offset1:14
	s_waitcnt lgkmcnt(2)
	v_mfma_f32_32x32x16_bf16 v[50:65], v[94:97], v[74:77], v[50:65]
	ds_read2_b64 v[90:93], v245 offset0:12 offset1:14
	s_waitcnt lgkmcnt(2)
	v_mfma_f32_32x32x16_bf16 v[2:17], v[82:85], v[78:81], v[2:17]
	ds_read2_b64 v[94:97], v246 offset0:12 offset1:14
	s_waitcnt lgkmcnt(2)
	v_mfma_f32_32x32x16_bf16 v[18:33], v[86:89], v[78:81], v[18:33]
	s_waitcnt lgkmcnt(1)
	v_mfma_f32_32x32x16_bf16 v[34:49], v[90:93], v[78:81], v[34:49]
	s_waitcnt lgkmcnt(0)
	v_mfma_f32_32x32x16_bf16 v[50:65], v[94:97], v[78:81], v[50:65]
.Lat_x_nopv:
	s_cmp_gt_i32 s22, s25
	s_cbranch_scc1 .Lat_x_noqk
	s_waitcnt lgkmcnt(4)
	v_mfma_f32_32x32x16_bf16 v[66:81], v[162:165], v[98:101], 0
	v_mfma_f32_32x32x16_bf16 v[82:97], v[166:169], v[98:101], 0
	ds_read_b128 v[186:189], v0 offset:96
	ds_read_b128 v[190:193], v0 offset:12896
	s_waitcnt lgkmcnt(4)
	v_mfma_f32_32x32x16_bf16 v[66:81], v[170:173], v[102:105], v[66:81]
	v_mfma_f32_32x32x16_bf16 v[82:97], v[174:177], v[102:105], v[82:97]
	ds_read_b128 v[162:165], v0 offset:128
	ds_read_b128 v[166:169], v0 offset:12928
	s_waitcnt lgkmcnt(4)
	v_mfma_f32_32x32x16_bf16 v[66:81], v[178:181], v[106:109], v[66:81]
	v_mfma_f32_32x32x16_bf16 v[82:97], v[182:185], v[106:109], v[82:97]
	ds_read_b128 v[170:173], v0 offset:160
	ds_read_b128 v[174:177], v0 offset:12960
	s_waitcnt lgkmcnt(4)
	v_mfma_f32_32x32x16_bf16 v[66:81], v[186:189], v[110:113], v[66:81]
	v_mfma_f32_32x32x16_bf16 v[82:97], v[190:193], v[110:113], v[82:97]
	ds_read_b128 v[178:181], v0 offset:192
	ds_read_b128 v[182:185], v0 offset:12992
	s_waitcnt lgkmcnt(4)
	v_mfma_f32_32x32x16_bf16 v[66:81], v[162:165], v[114:117], v[66:81]
	v_mfma_f32_32x32x16_bf16 v[82:97], v[166:169], v[114:117], v[82:97]
	ds_read_b128 v[186:189], v0 offset:224
	ds_read_b128 v[190:193], v0 offset:13024
	s_waitcnt lgkmcnt(4)
	v_mfma_f32_32x32x16_bf16 v[66:81], v[170:173], v[118:121], v[66:81]
	v_mfma_f32_32x32x16_bf16 v[82:97], v[174:177], v[118:121], v[82:97]
	ds_read_b128 v[162:165], v0 offset:256
	ds_read_b128 v[166:169], v0 offset:13056
	s_waitcnt lgkmcnt(4)
	v_mfma_f32_32x32x16_bf16 v[66:81], v[178:181], v[122:125], v[66:81]
	v_mfma_f32_32x32x16_bf16 v[82:97], v[182:185], v[122:125], v[82:97]
	ds_read_b128 v[170:173], v0 offset:288
	ds_read_b128 v[174:177], v0 offset:13088
	s_waitcnt lgkmcnt(4)
	v_mfma_f32_32x32x16_bf16 v[66:81], v[186:189], v[126:129], v[66:81]
	v_mfma_f32_32x32x16_bf16 v[82:97], v[190:193], v[126:129], v[82:97]
	ds_read_b128 v[178:181], v0 offset:320
	ds_read_b128 v[182:185], v0 offset:13120
	s_waitcnt lgkmcnt(4)
	v_mfma_f32_32x32x16_bf16 v[66:81], v[162:165], v[130:133], v[66:81]
	v_mfma_f32_32x32x16_bf16 v[82:97], v[166:169], v[130:133], v[82:97]
	ds_read_b128 v[186:189], v0 offset:352
	ds_read_b128 v[190:193], v0 offset:13152
	s_waitcnt lgkmcnt(4)
	v_mfma_f32_32x32x16_bf16 v[66:81], v[170:173], v[134:137], v[66:81]
	v_mfma_f32_32x32x16_bf16 v[82:97], v[174:177], v[134:137], v[82:97]
	s_waitcnt lgkmcnt(2)
	v_mfma_f32_32x32x16_bf16 v[66:81], v[178:181], v[138:141], v[66:81]
	v_mfma_f32_32x32x16_bf16 v[82:97], v[182:185], v[138:141], v[82:97]
	s_waitcnt lgkmcnt(0)
	v_mfma_f32_32x32x16_bf16 v[66:81], v[186:189], v[142:145], v[66:81]
	v_mfma_f32_32x32x16_bf16 v[82:97], v[190:193], v[142:145], v[82:97]
	s_lshl_b32 s39, s24, 8
	v_add_u32_e32 v0, s39, v232
	ds_read_b128 v[162:165], v0
	ds_read_b128 v[166:169], v0 offset:32
	ds_read_b128 v[170:173], v0 offset:64
	ds_read_b128 v[174:177], v0 offset:96
	ds_read_b128 v[178:181], v0 offset:128
	ds_read_b128 v[182:185], v0 offset:160
	ds_read_b128 v[186:189], v0 offset:192
	ds_read_b128 v[190:193], v0 offset:224
	s_branch .Lat_x_pref

.Lat_x_pf:
	s_lshl_b32 s65, s34, 5
	s_add_i32 s5, s65, s4
	v_add_u32_e32 v0, s5, v240
	v_min_u32_e32 v0, 0x80f, v0
	v_add_u32_e32 v0, s38, v0
	s_movk_i32 s39, 0xc00
	v_mul_lo_u32 v247, v0, s39
	v_lshl_add_u32 v247, v241, 4, v247
	v_lshlrev_b32_e32 v242, 5, v0
	global_load_dwordx4 v[98:101], v247, s[40:41]
	global_load_dwordx4 v[102:105], v247, s[40:41] offset:32
	global_load_dwordx4 v[106:109], v247, s[40:41] offset:64
	global_load_dwordx4 v[110:113], v247, s[40:41] offset:96
	global_load_dwordx4 v[114:117], v247, s[40:41] offset:128
	global_load_dwordx4 v[118:121], v247, s[40:41] offset:160
	global_load_dwordx4 v[122:125], v247, s[40:41] offset:192
	global_load_dwordx4 v[126:129], v247, s[40:41] offset:224
	global_load_dwordx4 v[130:133], v247, s[40:41] offset:256
	global_load_dwordx4 v[134:137], v247, s[40:41] offset:288
	global_load_dwordx4 v[138:141], v247, s[40:41] offset:320
	global_load_dwordx4 v[142:145], v247, s[40:41] offset:352
	s_lshl_b32 s36, s30, 2
	s_add_u32 s36, s36, 0x1507a400
	s_add_u32 s36, s48, s36
	s_addc_u32 s37, s49, 0
	global_load_dword v249, v242, s[36:37]
	s_lshl_b32 s73, s38, 11
	s_add_u32 s72, s73, 0x10480000
	s_lshl_b32 s73, s30, 8
	s_add_u32 s72, s72, s73
	s_add_u32 s8, s48, s72
	s_addc_u32 s9, s49, 0
	s_add_u32 s10, s8, 0x10000
	s_addc_u32 s11, s9, 0
	s_lshl_b32 s73, s38, 7
	s_add_u32 s72, s73, 0x14da0000
	s_add_u32 s12, s48, s72
	s_addc_u32 s13, s49, 0
	s_mul_i32 s73, s30, 0x410000
	s_lshl_b32 s72, s38, 1
	s_add_u32 s72, s72, s73
	s_add_u32 s72, s72, 0x12500000
	s_add_u32 s14, s48, s72
	s_addc_u32 s15, s49, 0
	s_add_u32 s16, s14, 0x208000
	s_addc_u32 s17, s15, 0
	s_lshl_b32 s73, s38, 5
	s_add_u32 s72, s73, 0x150fc400
	s_lshl_b32 s73, s30, 2
	s_add_u32 s72, s72, s73
	s_add_u32 s18, s48, s72
	s_addc_u32 s19, s49, 0
	s_lshl_b32 s73, s38, 2
	s_add_u32 s72, s73, 0x1506a000
	s_add_u32 s20, s48, s72
	s_addc_u32 s21, s49, 0
	global_load_dwordx4 v[198:201], v220, s[8:9]
	global_load_dwordx4 v[202:205], v220, s[10:11]
	global_load_dwordx4 v[206:209], v221, s[12:13]
	global_load_dwordx4 v[210:213], v222, s[14:15]
	global_load_dwordx4 v[214:217], v222, s[16:17]
	s_cmp_lg_u32 s34, 0
	s_cbranch_scc1 .Lat_nosq13
	v_lshl_add_u32 v247, v241, 5, v240
	v_lshlrev_b32_e32 v242, 2, v247
	v_lshlrev_b32_e32 v247, 5, v247
	global_load_dword v218, v247, s[18:19]
	global_load_dword v219, v242, s[20:21]
.Lat_nosq13:
.Lat_x_nopf:
	s_cmp_lg_u32 s35, 0
	s_cbranch_scc1 .Lat_ya_skip
	s_mov_b32 s96, s22
	s_cmp_gt_i32 s96, s25
	s_cbranch_scc1 .Lat_y_skip_a
	s_nop 7
	s_waitcnt lgkmcnt(0)
	v_mul_f32_e32 v66, v66, v162
	v_mul_f32_e32 v67, v67, v163
	v_mul_f32_e32 v68, v68, v164
	v_mul_f32_e32 v69, v69, v165
	v_mul_f32_e32 v70, v70, v166
	v_mul_f32_e32 v71, v71, v167
	v_mul_f32_e32 v72, v72, v168
	v_mul_f32_e32 v73, v73, v169
	v_mul_f32_e32 v74, v74, v170
	v_mul_f32_e32 v75, v75, v171
	v_mul_f32_e32 v76, v76, v172
	v_mul_f32_e32 v77, v77, v173
	v_mul_f32_e32 v78, v78, v174
	v_mul_f32_e32 v79, v79, v175
	v_mul_f32_e32 v80, v80, v176
	v_mul_f32_e32 v81, v81, v177
	v_mul_f32_e32 v82, v82, v178
	v_mul_f32_e32 v83, v83, v179
	v_mul_f32_e32 v84, v84, v180
	v_mul_f32_e32 v85, v85, v181
	v_mul_f32_e32 v86, v86, v182
	v_mul_f32_e32 v87, v87, v183
	v_mul_f32_e32 v88, v88, v184
	v_mul_f32_e32 v89, v89, v185
	v_mul_f32_e32 v90, v90, v186
	v_mul_f32_e32 v91, v91, v187
	v_mul_f32_e32 v92, v92, v188
	v_mul_f32_e32 v93, v93, v189
	v_mul_f32_e32 v94, v94, v190
	v_mul_f32_e32 v95, v95, v191
	v_mul_f32_e32 v96, v96, v192
	v_mul_f32_e32 v97, v97, v193
	s_cmp_lg_u32 s96, s25
	s_cbranch_scc1 .Lat_y_nogate_a
	v_add_u32_e32 v243, s38, v234
	v_lshlrev_b32_e32 v243, 11, v243
	v_lshl_add_u32 v243, v241, 3, v243
	global_load_dwordx2 v[162:163], v243, s[6:7] offset:0
	global_load_dwordx2 v[164:165], v243, s[6:7] offset:16
	global_load_dwordx2 v[166:167], v243, s[6:7] offset:32
	global_load_dwordx2 v[168:169], v243, s[6:7] offset:48
	global_load_dwordx2 v[170:171], v243, s[6:7] offset:64
	global_load_dwordx2 v[172:173], v243, s[6:7] offset:80
	global_load_dwordx2 v[174:175], v243, s[6:7] offset:96
	global_load_dwordx2 v[176:177], v243, s[6:7] offset:112
	global_load_dwordx2 v[178:179], v243, s[6:7] offset:128
	global_load_dwordx2 v[180:181], v243, s[6:7] offset:144
	global_load_dwordx2 v[182:183], v243, s[6:7] offset:160
	global_load_dwordx2 v[184:185], v243, s[6:7] offset:176
	global_load_dwordx2 v[186:187], v243, s[6:7] offset:192
	global_load_dwordx2 v[188:189], v243, s[6:7] offset:208
	global_load_dwordx2 v[190:191], v243, s[6:7] offset:224
	global_load_dwordx2 v[192:193], v243, s[6:7] offset:240

.Lat_yz:
	s_add_i32 s22, s22, 1
	s_add_i32 s24, s24, 1
	s_cmp_eq_u32 s24, 3
	s_cselect_b32 s24, 0, s24
	s_cmp_lt_u32 s22, s23
	s_cbranch_scc1 .Lat_loop
	s_cmp_eq_u32 s35, 0
	s_cbranch_scc1 .Lat_yc_skip
	s_add_i32 s96, s23, -1
	s_cmp_gt_i32 s96, s25
	s_cbranch_scc1 .Lat_y_skip_c
	s_nop 7
	s_waitcnt lgkmcnt(0)
	v_mul_f32_e32 v66, v66, v162
	v_mul_f32_e32 v67, v67, v163
	v_mul_f32_e32 v68, v68, v164
	v_mul_f32_e32 v69, v69, v165
	v_mul_f32_e32 v70, v70, v166
	v_mul_f32_e32 v71, v71, v167
	v_mul_f32_e32 v72, v72, v168
	v_mul_f32_e32 v73, v73, v169
	v_mul_f32_e32 v74, v74, v170
	v_mul_f32_e32 v75, v75, v171
	v_mul_f32_e32 v76, v76, v172
	v_mul_f32_e32 v77, v77, v173
	v_mul_f32_e32 v78, v78, v174
	v_mul_f32_e32 v79, v79, v175
	v_mul_f32_e32 v80, v80, v176
	v_mul_f32_e32 v81, v81, v177
	v_mul_f32_e32 v82, v82, v178
	v_mul_f32_e32 v83, v83, v179
	v_mul_f32_e32 v84, v84, v180
	v_mul_f32_e32 v85, v85, v181
	v_mul_f32_e32 v86, v86, v182
	v_mul_f32_e32 v87, v87, v183
	v_mul_f32_e32 v88, v88, v184
	v_mul_f32_e32 v89, v89, v185
	v_mul_f32_e32 v90, v90, v186
	v_mul_f32_e32 v91, v91, v187
	v_mul_f32_e32 v92, v92, v188
	v_mul_f32_e32 v93, v93, v189
	v_mul_f32_e32 v94, v94, v190
	v_mul_f32_e32 v95, v95, v191
	v_mul_f32_e32 v96, v96, v192
	v_mul_f32_e32 v97, v97, v193
	s_cmp_lg_u32 s96, s25
	s_cbranch_scc1 .Lat_y_nogate_c
	v_add_u32_e32 v243, s38, v234
	v_lshlrev_b32_e32 v243, 11, v243
	v_lshl_add_u32 v243, v241, 3, v243
	global_load_dwordx2 v[162:163], v243, s[6:7] offset:0
	global_load_dwordx2 v[164:165], v243, s[6:7] offset:16
	global_load_dwordx2 v[166:167], v243, s[6:7] offset:32
	global_load_dwordx2 v[168:169], v243, s[6:7] offset:48
	global_load_dwordx2 v[170:171], v243, s[6:7] offset:64
	global_load_dwordx2 v[172:173], v243, s[6:7] offset:80
	global_load_dwordx2 v[174:175], v243, s[6:7] offset:96
	global_load_dwordx2 v[176:177], v243, s[6:7] offset:112
	global_load_dwordx2 v[178:179], v243, s[6:7] offset:128
	global_load_dwordx2 v[180:181], v243, s[6:7] offset:144
	global_load_dwordx2 v[182:183], v243, s[6:7] offset:160
	global_load_dwordx2 v[184:185], v243, s[6:7] offset:176
	global_load_dwordx2 v[186:187], v243, s[6:7] offset:192
	global_load_dwordx2 v[188:189], v243, s[6:7] offset:208
	global_load_dwordx2 v[190:191], v243, s[6:7] offset:224
	global_load_dwordx2 v[192:193], v243, s[6:7] offset:240
